# K-rotation plus LDS-DMA pieces spread over more MFMA groups (2,2,2 after the barrier and 1,1 in the next half-step) now that DMA latency is lower
# baseline (speedup 1.0000x reference)
.LBB0_263:
	s_and_b32 s15, s14, 0x8000
	s_add_i32 s14, s14, 0x8000
	v_add3_u32 v142, v137, v138, s15
	v_add3_u32 v143, v136, v141, s15
	v_add3_u32 v144, v136, v138, s15
	s_waitcnt lgkmcnt(3)
	v_mfma_f32_16x16x32_bf16 v[124:127], v[174:177], v[158:161], v[124:127]
	v_mfma_f32_16x16x32_bf16 v[92:95], v[178:181], v[158:161], v[92:95]
	v_mfma_f32_16x16x32_bf16 v[60:63], v[182:185], v[158:161], v[60:63]
	v_mfma_f32_16x16x32_bf16 v[28:31], v[186:189], v[158:161], v[28:31]
	ds_read_b128 v[158:161], v143 offset:16384
	ds_read_b128 v[190:193], v142
	s_add_u32 s82, vcc_lo, 0x7930080
	s_addc_u32 s83, 0, 0
	s_add_i32 m0, s100, 0x6000
	v_lshl_add_u64 v[146:147], v[128:129], 0, s[82:83]
	global_load_lds_dwordx4 v[146:147], off
	s_waitcnt lgkmcnt(4)
	v_mfma_f32_16x16x32_bf16 v[120:123], v[174:177], v[162:165], v[120:123]
	v_mfma_f32_16x16x32_bf16 v[88:91], v[178:181], v[162:165], v[88:91]
	v_mfma_f32_16x16x32_bf16 v[56:59], v[182:185], v[162:165], v[56:59]
	v_mfma_f32_16x16x32_bf16 v[24:27], v[186:189], v[162:165], v[24:27]
	ds_read_b128 v[162:165], v143 offset:18432
	ds_read_b128 v[194:197], v142 offset:2048
	s_add_u32 s82, vcc_lo, s64
	s_addc_u32 s83, 0, s65
	s_add_i32 m0, s101, 0x6000
	v_lshl_add_u64 v[146:147], v[130:131], 0, s[82:83]
	global_load_lds_dwordx4 v[146:147], off
	s_waitcnt lgkmcnt(5)
	v_mfma_f32_16x16x32_bf16 v[116:119], v[174:177], v[166:169], v[116:119]
	v_mfma_f32_16x16x32_bf16 v[84:87], v[178:181], v[166:169], v[84:87]
	v_mfma_f32_16x16x32_bf16 v[52:55], v[182:185], v[166:169], v[52:55]
	v_mfma_f32_16x16x32_bf16 v[20:23], v[186:189], v[166:169], v[20:23]
	ds_read_b128 v[166:169], v143 offset:20480
	ds_read_b128 v[198:201], v142 offset:4096
	s_waitcnt lgkmcnt(6)
	v_mfma_f32_16x16x32_bf16 v[112:115], v[174:177], v[170:173], v[112:115]
	v_mfma_f32_16x16x32_bf16 v[80:83], v[178:181], v[170:173], v[80:83]
	v_mfma_f32_16x16x32_bf16 v[48:51], v[182:185], v[170:173], v[48:51]
	v_mfma_f32_16x16x32_bf16 v[16:19], v[186:189], v[170:173], v[16:19]
	ds_read_b128 v[170:173], v143 offset:22528
	ds_read_b128 v[150:153], v142 offset:6144
	s_waitcnt lgkmcnt(7)
	v_mfma_f32_16x16x32_bf16 v[108:111], v[174:177], v[158:161], v[108:111]
	v_mfma_f32_16x16x32_bf16 v[76:79], v[178:181], v[158:161], v[76:79]
	v_mfma_f32_16x16x32_bf16 v[44:47], v[182:185], v[158:161], v[44:47]
	v_mfma_f32_16x16x32_bf16 v[12:15], v[186:189], v[158:161], v[12:15]
	ds_read_b128 v[158:161], v144
	s_waitcnt lgkmcnt(6)
	v_mfma_f32_16x16x32_bf16 v[104:107], v[174:177], v[162:165], v[104:107]
	v_mfma_f32_16x16x32_bf16 v[72:75], v[178:181], v[162:165], v[72:75]
	v_mfma_f32_16x16x32_bf16 v[40:43], v[182:185], v[162:165], v[40:43]
	v_mfma_f32_16x16x32_bf16 v[8:11], v[186:189], v[162:165], v[8:11]
	ds_read_b128 v[162:165], v144 offset:2048
	s_waitcnt lgkmcnt(5)
	v_mfma_f32_16x16x32_bf16 v[100:103], v[174:177], v[166:169], v[100:103]
	v_mfma_f32_16x16x32_bf16 v[68:71], v[178:181], v[166:169], v[68:71]
	v_mfma_f32_16x16x32_bf16 v[36:39], v[182:185], v[166:169], v[36:39]
	v_mfma_f32_16x16x32_bf16 v[4:7], v[186:189], v[166:169], v[4:7]
	ds_read_b128 v[166:169], v144 offset:4096
	s_waitcnt lgkmcnt(4)
	v_mfma_f32_16x16x32_bf16 v[96:99], v[174:177], v[170:173], v[96:99]
	v_mfma_f32_16x16x32_bf16 v[64:67], v[178:181], v[170:173], v[64:67]
	v_mfma_f32_16x16x32_bf16 v[32:35], v[182:185], v[170:173], v[32:35]
	v_mfma_f32_16x16x32_bf16 v[0:3], v[186:189], v[170:173], v[0:3]
	ds_read_b128 v[170:173], v144 offset:6144
	s_waitcnt lgkmcnt(3)
	v_mfma_f32_16x16x32_bf16 v[124:127], v[190:193], v[158:161], v[124:127]
	v_mfma_f32_16x16x32_bf16 v[92:95], v[194:197], v[158:161], v[92:95]
	v_mfma_f32_16x16x32_bf16 v[60:63], v[198:201], v[158:161], v[60:63]
	v_mfma_f32_16x16x32_bf16 v[28:31], v[150:153], v[158:161], v[28:31]
	ds_read_b128 v[158:161], v144 offset:16384
	s_waitcnt lgkmcnt(3)
	v_mfma_f32_16x16x32_bf16 v[120:123], v[190:193], v[162:165], v[120:123]
	v_mfma_f32_16x16x32_bf16 v[88:91], v[194:197], v[162:165], v[88:91]
	v_mfma_f32_16x16x32_bf16 v[56:59], v[198:201], v[162:165], v[56:59]
	v_mfma_f32_16x16x32_bf16 v[24:27], v[150:153], v[162:165], v[24:27]
	ds_read_b128 v[162:165], v144 offset:18432
	s_waitcnt lgkmcnt(3)
	v_mfma_f32_16x16x32_bf16 v[116:119], v[190:193], v[166:169], v[116:119]
	v_mfma_f32_16x16x32_bf16 v[84:87], v[194:197], v[166:169], v[84:87]
	v_mfma_f32_16x16x32_bf16 v[52:55], v[198:201], v[166:169], v[52:55]
	v_mfma_f32_16x16x32_bf16 v[20:23], v[150:153], v[166:169], v[20:23]
	ds_read_b128 v[166:169], v144 offset:20480
	s_waitcnt lgkmcnt(3)
	v_mfma_f32_16x16x32_bf16 v[112:115], v[190:193], v[170:173], v[112:115]
	v_mfma_f32_16x16x32_bf16 v[80:83], v[194:197], v[170:173], v[80:83]
	v_mfma_f32_16x16x32_bf16 v[48:51], v[198:201], v[170:173], v[48:51]
	v_mfma_f32_16x16x32_bf16 v[16:19], v[150:153], v[170:173], v[16:19]
	ds_read_b128 v[170:173], v144 offset:22528
	s_waitcnt lgkmcnt(3)
	v_mfma_f32_16x16x32_bf16 v[108:111], v[190:193], v[158:161], v[108:111]
	v_mfma_f32_16x16x32_bf16 v[76:79], v[194:197], v[158:161], v[76:79]
	v_mfma_f32_16x16x32_bf16 v[44:47], v[198:201], v[158:161], v[44:47]
	v_mfma_f32_16x16x32_bf16 v[12:15], v[150:153], v[158:161], v[12:15]
	s_add_u32 s80, s80, 0x80
	s_addc_u32 s81, s81, 0
	s_cmpk_eq_i32 s80, 0xf80
	s_waitcnt vmcnt(0) lgkmcnt(0)
	s_barrier
	s_cbranch_scc1 .Lgemm_263_exit
	s_xor_b32 s22, s15, 0x8000
	v_add3_u32 v142, v137, v141, s22
	v_add3_u32 v143, v136, v141, s22
	ds_read_b128 v[174:177], v142
	ds_read_b128 v[178:181], v142 offset:2048
	ds_read_b128 v[182:185], v142 offset:4096
	ds_read_b128 v[186:189], v142 offset:6144
	ds_read_b128 v[158:161], v143
	s_add_i32 s100, s98, s15
	s_add_i32 s101, s99, s15
	s_lshr_b32 s22, s23, 3
	s_and_b32 s22, s22, 7
	s_lshl_b32 s22, s22, 9
	s_add_i32 vcc_lo, s80, s22
	s_cmp_ge_u32 vcc_lo, 0xf80
	s_cselect_b32 vcc_hi, 0xf80, 0
	s_sub_i32 vcc_lo, vcc_lo, vcc_hi
	v_mfma_f32_16x16x32_bf16 v[104:107], v[190:193], v[162:165], v[104:107]
	v_mfma_f32_16x16x32_bf16 v[72:75], v[194:197], v[162:165], v[72:75]
	v_mfma_f32_16x16x32_bf16 v[40:43], v[198:201], v[162:165], v[40:43]
	v_mfma_f32_16x16x32_bf16 v[8:11], v[150:153], v[162:165], v[8:11]
	ds_read_b128 v[162:165], v143 offset:2048
	s_add_u32 s82, vcc_lo, 0x7870080
	s_addc_u32 s83, 0, 0
	s_add_i32 m0, s100, 0x0
	v_lshl_add_u64 v[146:147], v[128:129], 0, s[82:83]
	global_load_lds_dwordx4 v[146:147], off
	s_add_u32 s82, vcc_lo, s58
	s_addc_u32 s83, 0, s59
	s_add_i32 m0, s101, 0x0
	v_lshl_add_u64 v[146:147], v[130:131], 0, s[82:83]
	global_load_lds_dwordx4 v[146:147], off
	v_mfma_f32_16x16x32_bf16 v[100:103], v[190:193], v[166:169], v[100:103]
	v_mfma_f32_16x16x32_bf16 v[68:71], v[194:197], v[166:169], v[68:71]
	v_mfma_f32_16x16x32_bf16 v[36:39], v[198:201], v[166:169], v[36:39]
	v_mfma_f32_16x16x32_bf16 v[4:7], v[150:153], v[166:169], v[4:7]
	ds_read_b128 v[166:169], v143 offset:4096
	s_add_u32 s82, vcc_lo, 0x78b0080
	s_addc_u32 s83, 0, 0
	s_add_i32 m0, s100, 0x2000
	v_lshl_add_u64 v[146:147], v[128:129], 0, s[82:83]
	global_load_lds_dwordx4 v[146:147], off
	s_add_u32 s82, vcc_lo, s60
	s_addc_u32 s83, 0, s61
	s_add_i32 m0, s101, 0x2000
	v_lshl_add_u64 v[146:147], v[130:131], 0, s[82:83]
	global_load_lds_dwordx4 v[146:147], off
	v_mfma_f32_16x16x32_bf16 v[96:99], v[190:193], v[170:173], v[96:99]
	v_mfma_f32_16x16x32_bf16 v[64:67], v[194:197], v[170:173], v[64:67]
	v_mfma_f32_16x16x32_bf16 v[32:35], v[198:201], v[170:173], v[32:35]
	v_mfma_f32_16x16x32_bf16 v[0:3], v[150:153], v[170:173], v[0:3]
	ds_read_b128 v[170:173], v143 offset:6144
	s_add_u32 s82, vcc_lo, 0x78f0080
	s_addc_u32 s83, 0, 0
	s_add_i32 m0, s100, 0x4000
	v_lshl_add_u64 v[146:147], v[128:129], 0, s[82:83]
	global_load_lds_dwordx4 v[146:147], off
	s_add_u32 s82, vcc_lo, s62
	s_addc_u32 s83, 0, s63
	s_add_i32 m0, s101, 0x4000
	v_lshl_add_u64 v[146:147], v[130:131], 0, s[82:83]
	global_load_lds_dwordx4 v[146:147], off
	s_branch .LBB0_263

.LBB0_496:
	s_and_b32 s70, s4, 0x8000
	s_add_i32 s4, s4, 0x8000
	v_add3_u32 v143, v137, v138, s70
	v_add3_u32 v157, v139, v142, s70
	v_add3_u32 v186, v139, v138, s70
	s_waitcnt lgkmcnt(3)
	v_mfma_f32_16x16x32_bf16 v[124:127], v[174:177], v[158:161], v[124:127]
	v_mfma_f32_16x16x32_bf16 v[96:99], v[178:181], v[158:161], v[96:99]
	v_mfma_f32_16x16x32_bf16 v[72:75], v[182:185], v[158:161], v[72:75]
	v_mfma_f32_16x16x32_bf16 v[48:51], v[144:147], v[158:161], v[48:51]
	ds_read_b128 v[158:161], v157 offset:16384
	ds_read_b128 v[148:151], v143
	s_add_u32 s68, vcc_lo, s56
	s_addc_u32 s69, 0, s57
	s_add_i32 m0, s76, 0x6000
	v_lshl_add_u64 v[242:243], v[128:129], 0, s[68:69]
	global_load_lds_dwordx4 v[242:243], off
	s_waitcnt lgkmcnt(4)
	v_mfma_f32_16x16x32_bf16 v[120:123], v[174:177], v[162:165], v[120:123]
	v_mfma_f32_16x16x32_bf16 v[92:95], v[178:181], v[162:165], v[92:95]
	v_mfma_f32_16x16x32_bf16 v[68:71], v[182:185], v[162:165], v[68:71]
	v_mfma_f32_16x16x32_bf16 v[44:47], v[144:147], v[162:165], v[44:47]
	ds_read_b128 v[162:165], v157 offset:18432
	ds_read_b128 v[152:155], v143 offset:2048
	s_add_u32 s68, vcc_lo, s58
	s_addc_u32 s69, 0, s59
	s_add_i32 m0, s77, 0x6000
	v_lshl_add_u64 v[242:243], v[130:131], 0, s[68:69]
	global_load_lds_dwordx4 v[242:243], off
	s_waitcnt lgkmcnt(5)
	v_mfma_f32_16x16x32_bf16 v[116:119], v[174:177], v[166:169], v[116:119]
	v_mfma_f32_16x16x32_bf16 v[88:91], v[178:181], v[166:169], v[88:91]
	v_mfma_f32_16x16x32_bf16 v[64:67], v[182:185], v[166:169], v[64:67]
	v_mfma_f32_16x16x32_bf16 v[40:43], v[144:147], v[166:169], v[40:43]
	ds_read_b128 v[166:169], v157 offset:20480
	ds_read_b128 v[244:247], v143 offset:4096
	s_waitcnt lgkmcnt(6)
	v_mfma_f32_16x16x32_bf16 v[112:115], v[174:177], v[170:173], v[112:115]
	v_mfma_f32_16x16x32_bf16 v[84:87], v[178:181], v[170:173], v[84:87]
	v_mfma_f32_16x16x32_bf16 v[60:63], v[182:185], v[170:173], v[60:63]
	v_mfma_f32_16x16x32_bf16 v[36:39], v[144:147], v[170:173], v[36:39]
	ds_read_b128 v[170:173], v157 offset:22528
	ds_read_b128 v[248:251], v143 offset:6144
	s_waitcnt lgkmcnt(7)
	v_mfma_f32_16x16x32_bf16 v[108:111], v[174:177], v[158:161], v[108:111]
	v_mfma_f32_16x16x32_bf16 v[80:83], v[178:181], v[158:161], v[80:83]
	v_mfma_f32_16x16x32_bf16 v[56:59], v[182:185], v[158:161], v[56:59]
	v_mfma_f32_16x16x32_bf16 v[32:35], v[144:147], v[158:161], v[32:35]
	ds_read_b128 v[158:161], v186
	s_waitcnt lgkmcnt(6)
	v_mfma_f32_16x16x32_bf16 v[28:31], v[174:177], v[162:165], v[28:31]
	v_mfma_f32_16x16x32_bf16 v[16:19], v[178:181], v[162:165], v[16:19]
	v_mfma_f32_16x16x32_bf16 v[8:11], v[182:185], v[162:165], v[8:11]
	v_mfma_f32_16x16x32_bf16 v[0:3], v[144:147], v[162:165], v[0:3]
	ds_read_b128 v[162:165], v186 offset:2048
	s_waitcnt lgkmcnt(5)
	v_mfma_f32_16x16x32_bf16 v[104:107], v[174:177], v[166:169], v[104:107]
	v_mfma_f32_16x16x32_bf16 v[76:79], v[178:181], v[166:169], v[76:79]
	v_mfma_f32_16x16x32_bf16 v[52:55], v[182:185], v[166:169], v[52:55]
	v_mfma_f32_16x16x32_bf16 v[100:103], v[144:147], v[166:169], v[100:103]
	ds_read_b128 v[166:169], v186 offset:4096
	s_waitcnt lgkmcnt(4)
	v_mfma_f32_16x16x32_bf16 v[24:27], v[174:177], v[170:173], v[24:27]
	v_mfma_f32_16x16x32_bf16 v[12:15], v[178:181], v[170:173], v[12:15]
	v_mfma_f32_16x16x32_bf16 v[4:7], v[182:185], v[170:173], v[4:7]
	v_mfma_f32_16x16x32_bf16 v[20:23], v[144:147], v[170:173], v[20:23]
	ds_read_b128 v[170:173], v186 offset:6144
	s_waitcnt lgkmcnt(3)
	v_mfma_f32_16x16x32_bf16 v[124:127], v[148:151], v[158:161], v[124:127]
	v_mfma_f32_16x16x32_bf16 v[96:99], v[152:155], v[158:161], v[96:99]
	v_mfma_f32_16x16x32_bf16 v[72:75], v[244:247], v[158:161], v[72:75]
	v_mfma_f32_16x16x32_bf16 v[48:51], v[248:251], v[158:161], v[48:51]
	ds_read_b128 v[158:161], v186 offset:16384
	s_waitcnt lgkmcnt(3)
	v_mfma_f32_16x16x32_bf16 v[120:123], v[148:151], v[162:165], v[120:123]
	v_mfma_f32_16x16x32_bf16 v[92:95], v[152:155], v[162:165], v[92:95]
	v_mfma_f32_16x16x32_bf16 v[68:71], v[244:247], v[162:165], v[68:71]
	v_mfma_f32_16x16x32_bf16 v[44:47], v[248:251], v[162:165], v[44:47]
	ds_read_b128 v[162:165], v186 offset:18432
	s_waitcnt lgkmcnt(3)
	v_mfma_f32_16x16x32_bf16 v[116:119], v[148:151], v[166:169], v[116:119]
	v_mfma_f32_16x16x32_bf16 v[88:91], v[152:155], v[166:169], v[88:91]
	v_mfma_f32_16x16x32_bf16 v[64:67], v[244:247], v[166:169], v[64:67]
	v_mfma_f32_16x16x32_bf16 v[40:43], v[248:251], v[166:169], v[40:43]
	ds_read_b128 v[166:169], v186 offset:20480
	s_waitcnt lgkmcnt(3)
	v_mfma_f32_16x16x32_bf16 v[112:115], v[148:151], v[170:173], v[112:115]
	v_mfma_f32_16x16x32_bf16 v[84:87], v[152:155], v[170:173], v[84:87]
	v_mfma_f32_16x16x32_bf16 v[60:63], v[244:247], v[170:173], v[60:63]
	v_mfma_f32_16x16x32_bf16 v[36:39], v[248:251], v[170:173], v[36:39]
	ds_read_b128 v[170:173], v186 offset:22528
	s_waitcnt lgkmcnt(3)
	v_mfma_f32_16x16x32_bf16 v[108:111], v[148:151], v[158:161], v[108:111]
	v_mfma_f32_16x16x32_bf16 v[80:83], v[152:155], v[158:161], v[80:83]
	v_mfma_f32_16x16x32_bf16 v[56:59], v[244:247], v[158:161], v[56:59]
	v_mfma_f32_16x16x32_bf16 v[32:35], v[248:251], v[158:161], v[32:35]
	s_add_u32 s62, s62, 0x80
	s_addc_u32 s63, s63, 0
	s_cmpk_eq_i32 s62, 0xf80
	s_waitcnt vmcnt(0) lgkmcnt(0)
	s_barrier
	s_cbranch_scc1 .Lgemm_496_exit
	s_xor_b32 s71, s70, 0x8000
	v_add3_u32 v143, v137, v142, s71
	v_add3_u32 v157, v139, v142, s71
	ds_read_b128 v[174:177], v143
	ds_read_b128 v[178:181], v143 offset:2048
	ds_read_b128 v[182:185], v143 offset:4096
	ds_read_b128 v[144:147], v143 offset:6144
	ds_read_b128 v[158:161], v157
	s_add_i32 s76, s66, s70
	s_add_i32 s77, s67, s70
	s_lshr_b32 s71, s23, 3
	s_and_b32 s71, s71, 31
	s_cmp_eq_u32 s71, 31
	s_cselect_b32 s71, 0, s71
	s_lshl_b32 s71, s71, 7
	s_add_i32 vcc_lo, s62, s71
	s_cmp_ge_u32 vcc_lo, 0xf80
	s_cselect_b32 vcc_hi, 0xf80, 0
	s_sub_i32 vcc_lo, vcc_lo, vcc_hi
	v_mfma_f32_16x16x32_bf16 v[28:31], v[148:151], v[162:165], v[28:31]
	v_mfma_f32_16x16x32_bf16 v[16:19], v[152:155], v[162:165], v[16:19]
	v_mfma_f32_16x16x32_bf16 v[8:11], v[244:247], v[162:165], v[8:11]
	v_mfma_f32_16x16x32_bf16 v[0:3], v[248:251], v[162:165], v[0:3]
	ds_read_b128 v[162:165], v157 offset:2048
	s_add_u32 s68, vcc_lo, s38
	s_addc_u32 s69, 0, s39
	s_add_i32 m0, s76, 0x0
	v_lshl_add_u64 v[242:243], v[128:129], 0, s[68:69]
	global_load_lds_dwordx4 v[242:243], off
	s_add_u32 s68, vcc_lo, s40
	s_addc_u32 s69, 0, s41
	s_add_i32 m0, s77, 0x0
	v_lshl_add_u64 v[242:243], v[130:131], 0, s[68:69]
	global_load_lds_dwordx4 v[242:243], off
	v_mfma_f32_16x16x32_bf16 v[104:107], v[148:151], v[166:169], v[104:107]
	v_mfma_f32_16x16x32_bf16 v[76:79], v[152:155], v[166:169], v[76:79]
	v_mfma_f32_16x16x32_bf16 v[52:55], v[244:247], v[166:169], v[52:55]
	v_mfma_f32_16x16x32_bf16 v[100:103], v[248:251], v[166:169], v[100:103]
	ds_read_b128 v[166:169], v157 offset:4096
	s_add_u32 s68, vcc_lo, s44
	s_addc_u32 s69, 0, s45
	s_add_i32 m0, s76, 0x2000
	v_lshl_add_u64 v[242:243], v[128:129], 0, s[68:69]
	global_load_lds_dwordx4 v[242:243], off
	s_add_u32 s68, vcc_lo, s48
	s_addc_u32 s69, 0, s49
	s_add_i32 m0, s77, 0x2000
	v_lshl_add_u64 v[242:243], v[130:131], 0, s[68:69]
	global_load_lds_dwordx4 v[242:243], off
	v_mfma_f32_16x16x32_bf16 v[24:27], v[148:151], v[170:173], v[24:27]
	v_mfma_f32_16x16x32_bf16 v[12:15], v[152:155], v[170:173], v[12:15]
	v_mfma_f32_16x16x32_bf16 v[4:7], v[244:247], v[170:173], v[4:7]
	v_mfma_f32_16x16x32_bf16 v[20:23], v[248:251], v[170:173], v[20:23]
	ds_read_b128 v[170:173], v157 offset:6144
	s_add_u32 s68, vcc_lo, s50
	s_addc_u32 s69, 0, s51
	s_add_i32 m0, s76, 0x4000
	v_lshl_add_u64 v[242:243], v[128:129], 0, s[68:69]
	global_load_lds_dwordx4 v[242:243], off
	s_add_u32 s68, vcc_lo, s54
	s_addc_u32 s69, 0, s55
	s_add_i32 m0, s77, 0x4000
	v_lshl_add_u64 v[242:243], v[130:131], 0, s[68:69]
	global_load_lds_dwordx4 v[242:243], off
	s_branch .LBB0_496

.LBB0_621:
	s_and_b32 s68, s60, 0x8000
	s_add_i32 s60, s60, 0x8000
	v_add3_u32 v143, v137, v138, s68
	v_add3_u32 v157, v139, v140, s68
	v_add3_u32 v186, v139, v138, s68
	s_waitcnt lgkmcnt(3)
	v_mfma_f32_16x16x32_bf16 v[124:127], v[174:177], v[158:161], v[124:127]
	v_mfma_f32_16x16x32_bf16 v[108:111], v[178:181], v[158:161], v[108:111]
	v_mfma_f32_16x16x32_bf16 v[92:95], v[182:185], v[158:161], v[92:95]
	v_mfma_f32_16x16x32_bf16 v[76:79], v[144:147], v[158:161], v[76:79]
	ds_read_b128 v[158:161], v157 offset:16384
	ds_read_b128 v[148:151], v143
	s_add_u32 s66, vcc_lo, s50
	s_addc_u32 s67, 0, s51
	s_add_i32 m0, s70, 0x6000
	v_lshl_add_u64 v[242:243], v[128:129], 0, s[66:67]
	global_load_lds_dwordx4 v[242:243], off
	s_waitcnt lgkmcnt(4)
	v_mfma_f32_16x16x32_bf16 v[120:123], v[174:177], v[162:165], v[120:123]
	v_mfma_f32_16x16x32_bf16 v[104:107], v[178:181], v[162:165], v[104:107]
	v_mfma_f32_16x16x32_bf16 v[88:91], v[182:185], v[162:165], v[88:91]
	v_mfma_f32_16x16x32_bf16 v[72:75], v[144:147], v[162:165], v[72:75]
	ds_read_b128 v[162:165], v157 offset:18432
	ds_read_b128 v[152:155], v143 offset:2048
	s_add_u32 s66, vcc_lo, s54
	s_addc_u32 s67, 0, s55
	s_add_i32 m0, s71, 0x6000
	v_lshl_add_u64 v[242:243], v[130:131], 0, s[66:67]
	global_load_lds_dwordx4 v[242:243], off
	s_waitcnt lgkmcnt(5)
	v_mfma_f32_16x16x32_bf16 v[116:119], v[174:177], v[166:169], v[116:119]
	v_mfma_f32_16x16x32_bf16 v[100:103], v[178:181], v[166:169], v[100:103]
	v_mfma_f32_16x16x32_bf16 v[84:87], v[182:185], v[166:169], v[84:87]
	v_mfma_f32_16x16x32_bf16 v[68:71], v[144:147], v[166:169], v[68:71]
	ds_read_b128 v[166:169], v157 offset:20480
	ds_read_b128 v[244:247], v143 offset:4096
	s_waitcnt lgkmcnt(6)
	v_mfma_f32_16x16x32_bf16 v[112:115], v[174:177], v[170:173], v[112:115]
	v_mfma_f32_16x16x32_bf16 v[96:99], v[178:181], v[170:173], v[96:99]
	v_mfma_f32_16x16x32_bf16 v[80:83], v[182:185], v[170:173], v[80:83]
	v_mfma_f32_16x16x32_bf16 v[64:67], v[144:147], v[170:173], v[64:67]
	ds_read_b128 v[170:173], v157 offset:22528
	ds_read_b128 v[248:251], v143 offset:6144
	s_waitcnt lgkmcnt(7)
	v_mfma_f32_16x16x32_bf16 v[60:63], v[174:177], v[158:161], v[60:63]
	v_mfma_f32_16x16x32_bf16 v[48:51], v[178:181], v[158:161], v[48:51]
	v_mfma_f32_16x16x32_bf16 v[40:43], v[182:185], v[158:161], v[40:43]
	v_mfma_f32_16x16x32_bf16 v[32:35], v[144:147], v[158:161], v[32:35]
	ds_read_b128 v[158:161], v186
	s_waitcnt lgkmcnt(6)
	v_mfma_f32_16x16x32_bf16 v[28:31], v[174:177], v[162:165], v[28:31]
	v_mfma_f32_16x16x32_bf16 v[16:19], v[178:181], v[162:165], v[16:19]
	v_mfma_f32_16x16x32_bf16 v[8:11], v[182:185], v[162:165], v[8:11]
	v_mfma_f32_16x16x32_bf16 v[0:3], v[144:147], v[162:165], v[0:3]
	ds_read_b128 v[162:165], v186 offset:2048
	s_waitcnt lgkmcnt(5)
	v_mfma_f32_16x16x32_bf16 v[52:55], v[174:177], v[166:169], v[52:55]
	v_mfma_f32_16x16x32_bf16 v[44:47], v[178:181], v[166:169], v[44:47]
	v_mfma_f32_16x16x32_bf16 v[36:39], v[182:185], v[166:169], v[36:39]
	v_mfma_f32_16x16x32_bf16 v[56:59], v[144:147], v[166:169], v[56:59]
	ds_read_b128 v[166:169], v186 offset:4096
	s_waitcnt lgkmcnt(4)
	v_mfma_f32_16x16x32_bf16 v[24:27], v[174:177], v[170:173], v[24:27]
	v_mfma_f32_16x16x32_bf16 v[12:15], v[178:181], v[170:173], v[12:15]
	v_mfma_f32_16x16x32_bf16 v[4:7], v[182:185], v[170:173], v[4:7]
	v_mfma_f32_16x16x32_bf16 v[20:23], v[144:147], v[170:173], v[20:23]
	ds_read_b128 v[170:173], v186 offset:6144
	s_waitcnt lgkmcnt(3)
	v_mfma_f32_16x16x32_bf16 v[124:127], v[148:151], v[158:161], v[124:127]
	v_mfma_f32_16x16x32_bf16 v[108:111], v[152:155], v[158:161], v[108:111]
	v_mfma_f32_16x16x32_bf16 v[92:95], v[244:247], v[158:161], v[92:95]
	v_mfma_f32_16x16x32_bf16 v[76:79], v[248:251], v[158:161], v[76:79]
	ds_read_b128 v[158:161], v186 offset:16384
	s_waitcnt lgkmcnt(3)
	v_mfma_f32_16x16x32_bf16 v[120:123], v[148:151], v[162:165], v[120:123]
	v_mfma_f32_16x16x32_bf16 v[104:107], v[152:155], v[162:165], v[104:107]
	v_mfma_f32_16x16x32_bf16 v[88:91], v[244:247], v[162:165], v[88:91]
	v_mfma_f32_16x16x32_bf16 v[72:75], v[248:251], v[162:165], v[72:75]
	ds_read_b128 v[162:165], v186 offset:18432
	s_waitcnt lgkmcnt(3)
	v_mfma_f32_16x16x32_bf16 v[116:119], v[148:151], v[166:169], v[116:119]
	v_mfma_f32_16x16x32_bf16 v[100:103], v[152:155], v[166:169], v[100:103]
	v_mfma_f32_16x16x32_bf16 v[84:87], v[244:247], v[166:169], v[84:87]
	v_mfma_f32_16x16x32_bf16 v[68:71], v[248:251], v[166:169], v[68:71]
	ds_read_b128 v[166:169], v186 offset:20480
	s_waitcnt lgkmcnt(3)
	v_mfma_f32_16x16x32_bf16 v[112:115], v[148:151], v[170:173], v[112:115]
	v_mfma_f32_16x16x32_bf16 v[96:99], v[152:155], v[170:173], v[96:99]
	v_mfma_f32_16x16x32_bf16 v[80:83], v[244:247], v[170:173], v[80:83]
	v_mfma_f32_16x16x32_bf16 v[64:67], v[248:251], v[170:173], v[64:67]
	ds_read_b128 v[170:173], v186 offset:22528
	s_waitcnt lgkmcnt(3)
	v_mfma_f32_16x16x32_bf16 v[60:63], v[148:151], v[158:161], v[60:63]
	v_mfma_f32_16x16x32_bf16 v[48:51], v[152:155], v[158:161], v[48:51]
	v_mfma_f32_16x16x32_bf16 v[40:43], v[244:247], v[158:161], v[40:43]
	v_mfma_f32_16x16x32_bf16 v[32:35], v[248:251], v[158:161], v[32:35]
	s_add_u32 s4, s4, 0x80
	s_addc_u32 s5, s5, 0
	s_cmpk_eq_i32 s4, 0xf80
	s_waitcnt vmcnt(0) lgkmcnt(0)
	s_barrier
	s_cbranch_scc1 .Lgemm_621_exit
	s_xor_b32 s69, s68, 0x8000
	v_add3_u32 v143, v137, v140, s69
	v_add3_u32 v157, v139, v140, s69
	ds_read_b128 v[174:177], v143
	ds_read_b128 v[178:181], v143 offset:2048
	ds_read_b128 v[182:185], v143 offset:4096
	ds_read_b128 v[144:147], v143 offset:6144
	ds_read_b128 v[158:161], v157
	s_add_i32 s70, s64, s68
	s_add_i32 s71, s65, s68
	s_lshr_b32 s69, s23, 3
	s_and_b32 s69, s69, 7
	s_lshl_b32 s69, s69, 9
	s_add_i32 vcc_lo, s4, s69
	s_cmp_ge_u32 vcc_lo, 0xf80
	s_cselect_b32 vcc_hi, 0xf80, 0
	s_sub_i32 vcc_lo, vcc_lo, vcc_hi
	v_mfma_f32_16x16x32_bf16 v[28:31], v[148:151], v[162:165], v[28:31]
	v_mfma_f32_16x16x32_bf16 v[16:19], v[152:155], v[162:165], v[16:19]
	v_mfma_f32_16x16x32_bf16 v[8:11], v[244:247], v[162:165], v[8:11]
	v_mfma_f32_16x16x32_bf16 v[0:3], v[248:251], v[162:165], v[0:3]
	ds_read_b128 v[162:165], v157 offset:2048
	s_add_u32 s66, vcc_lo, s36
	s_addc_u32 s67, 0, s37
	s_add_i32 m0, s70, 0x0
	v_lshl_add_u64 v[242:243], v[128:129], 0, s[66:67]
	global_load_lds_dwordx4 v[242:243], off
	s_add_u32 s66, vcc_lo, s38
	s_addc_u32 s67, 0, s39
	s_add_i32 m0, s71, 0x0
	v_lshl_add_u64 v[242:243], v[130:131], 0, s[66:67]
	global_load_lds_dwordx4 v[242:243], off
	v_mfma_f32_16x16x32_bf16 v[52:55], v[148:151], v[166:169], v[52:55]
	v_mfma_f32_16x16x32_bf16 v[44:47], v[152:155], v[166:169], v[44:47]
	v_mfma_f32_16x16x32_bf16 v[36:39], v[244:247], v[166:169], v[36:39]
	v_mfma_f32_16x16x32_bf16 v[56:59], v[248:251], v[166:169], v[56:59]
	ds_read_b128 v[166:169], v157 offset:4096
	s_add_u32 s66, vcc_lo, s40
	s_addc_u32 s67, 0, s41
	s_add_i32 m0, s70, 0x2000
	v_lshl_add_u64 v[242:243], v[128:129], 0, s[66:67]
	global_load_lds_dwordx4 v[242:243], off
	s_add_u32 s66, vcc_lo, s42
	s_addc_u32 s67, 0, s43
	s_add_i32 m0, s71, 0x2000
	v_lshl_add_u64 v[242:243], v[130:131], 0, s[66:67]
	global_load_lds_dwordx4 v[242:243], off
	v_mfma_f32_16x16x32_bf16 v[24:27], v[148:151], v[170:173], v[24:27]
	v_mfma_f32_16x16x32_bf16 v[12:15], v[152:155], v[170:173], v[12:15]
	v_mfma_f32_16x16x32_bf16 v[4:7], v[244:247], v[170:173], v[4:7]
	v_mfma_f32_16x16x32_bf16 v[20:23], v[248:251], v[170:173], v[20:23]
	ds_read_b128 v[170:173], v157 offset:6144
	s_add_u32 s66, vcc_lo, s44
	s_addc_u32 s67, 0, s45
	s_add_i32 m0, s70, 0x4000
	v_lshl_add_u64 v[242:243], v[128:129], 0, s[66:67]
	global_load_lds_dwordx4 v[242:243], off
	s_add_u32 s66, vcc_lo, s48
	s_addc_u32 s67, 0, s49
	s_add_i32 m0, s71, 0x4000
	v_lshl_add_u64 v[242:243], v[130:131], 0, s[66:67]
	global_load_lds_dwordx4 v[242:243], off
	s_branch .LBB0_621

.LBB0_698:
	s_and_b32 s59, s2, 0x8000
	s_add_i32 s2, s2, 0x8000
	v_add3_u32 v157, v138, v139, s59
	v_add3_u32 v186, v140, v143, s59
	v_add3_u32 v187, v140, v139, s59
	s_waitcnt lgkmcnt(3)
	v_mfma_f32_16x16x32_bf16 v[124:127], v[174:177], v[158:161], v[124:127]
	v_mfma_f32_16x16x32_bf16 v[108:111], v[178:181], v[158:161], v[108:111]
	v_mfma_f32_16x16x32_bf16 v[92:95], v[182:185], v[158:161], v[92:95]
	v_mfma_f32_16x16x32_bf16 v[76:79], v[144:147], v[158:161], v[76:79]
	ds_read_b128 v[158:161], v186 offset:16384
	ds_read_b128 v[148:151], v157
	s_add_u32 s60, vcc_lo, s44
	s_addc_u32 s61, 0, s45
	s_add_i32 m0, s63, 0x6000
	v_lshl_add_u64 v[242:243], v[130:131], 0, s[60:61]
	global_load_lds_dwordx4 v[242:243], off
	s_waitcnt lgkmcnt(4)
	v_mfma_f32_16x16x32_bf16 v[120:123], v[174:177], v[162:165], v[120:123]
	v_mfma_f32_16x16x32_bf16 v[104:107], v[178:181], v[162:165], v[104:107]
	v_mfma_f32_16x16x32_bf16 v[88:91], v[182:185], v[162:165], v[88:91]
	v_mfma_f32_16x16x32_bf16 v[72:75], v[144:147], v[162:165], v[72:75]
	ds_read_b128 v[162:165], v186 offset:18432
	ds_read_b128 v[152:155], v157 offset:2048
	s_add_u32 s60, vcc_lo, s48
	s_addc_u32 s61, 0, s49
	s_add_i32 m0, s64, 0x6000
	v_lshl_add_u64 v[242:243], v[132:133], 0, s[60:61]
	global_load_lds_dwordx4 v[242:243], off
	s_waitcnt lgkmcnt(5)
	v_mfma_f32_16x16x32_bf16 v[116:119], v[174:177], v[166:169], v[116:119]
	v_mfma_f32_16x16x32_bf16 v[100:103], v[178:181], v[166:169], v[100:103]
	v_mfma_f32_16x16x32_bf16 v[84:87], v[182:185], v[166:169], v[84:87]
	v_mfma_f32_16x16x32_bf16 v[68:71], v[144:147], v[166:169], v[68:71]
	ds_read_b128 v[166:169], v186 offset:20480
	ds_read_b128 v[244:247], v157 offset:4096
	s_waitcnt lgkmcnt(6)
	v_mfma_f32_16x16x32_bf16 v[112:115], v[174:177], v[170:173], v[112:115]
	v_mfma_f32_16x16x32_bf16 v[96:99], v[178:181], v[170:173], v[96:99]
	v_mfma_f32_16x16x32_bf16 v[80:83], v[182:185], v[170:173], v[80:83]
	v_mfma_f32_16x16x32_bf16 v[64:67], v[144:147], v[170:173], v[64:67]
	ds_read_b128 v[170:173], v186 offset:22528
	ds_read_b128 v[248:251], v157 offset:6144
	s_waitcnt lgkmcnt(7)
	v_mfma_f32_16x16x32_bf16 v[60:63], v[174:177], v[158:161], v[60:63]
	v_mfma_f32_16x16x32_bf16 v[36:39], v[178:181], v[158:161], v[36:39]
	v_mfma_f32_16x16x32_bf16 v[20:23], v[182:185], v[158:161], v[20:23]
	v_mfma_f32_16x16x32_bf16 v[4:7], v[144:147], v[158:161], v[4:7]
	ds_read_b128 v[158:161], v187
	s_waitcnt lgkmcnt(6)
	v_mfma_f32_16x16x32_bf16 v[56:59], v[174:177], v[162:165], v[56:59]
	v_mfma_f32_16x16x32_bf16 v[32:35], v[178:181], v[162:165], v[32:35]
	v_mfma_f32_16x16x32_bf16 v[16:19], v[182:185], v[162:165], v[16:19]
	v_mfma_f32_16x16x32_bf16 v[0:3], v[144:147], v[162:165], v[0:3]
	ds_read_b128 v[162:165], v187 offset:2048
	s_waitcnt lgkmcnt(5)
	v_mfma_f32_16x16x32_bf16 v[52:55], v[174:177], v[166:169], v[52:55]
	v_mfma_f32_16x16x32_bf16 v[28:31], v[178:181], v[166:169], v[28:31]
	v_mfma_f32_16x16x32_bf16 v[12:15], v[182:185], v[166:169], v[12:15]
	v_mfma_f32_16x16x32_bf16 v[44:47], v[144:147], v[166:169], v[44:47]
	ds_read_b128 v[166:169], v187 offset:4096
	s_waitcnt lgkmcnt(4)
	v_mfma_f32_16x16x32_bf16 v[48:51], v[174:177], v[170:173], v[48:51]
	v_mfma_f32_16x16x32_bf16 v[24:27], v[178:181], v[170:173], v[24:27]
	v_mfma_f32_16x16x32_bf16 v[8:11], v[182:185], v[170:173], v[8:11]
	v_mfma_f32_16x16x32_bf16 v[40:43], v[144:147], v[170:173], v[40:43]
	ds_read_b128 v[170:173], v187 offset:6144
	s_waitcnt lgkmcnt(3)
	v_mfma_f32_16x16x32_bf16 v[124:127], v[148:151], v[158:161], v[124:127]
	v_mfma_f32_16x16x32_bf16 v[108:111], v[152:155], v[158:161], v[108:111]
	v_mfma_f32_16x16x32_bf16 v[92:95], v[244:247], v[158:161], v[92:95]
	v_mfma_f32_16x16x32_bf16 v[76:79], v[248:251], v[158:161], v[76:79]
	ds_read_b128 v[158:161], v187 offset:16384
	s_waitcnt lgkmcnt(3)
	v_mfma_f32_16x16x32_bf16 v[120:123], v[148:151], v[162:165], v[120:123]
	v_mfma_f32_16x16x32_bf16 v[104:107], v[152:155], v[162:165], v[104:107]
	v_mfma_f32_16x16x32_bf16 v[88:91], v[244:247], v[162:165], v[88:91]
	v_mfma_f32_16x16x32_bf16 v[72:75], v[248:251], v[162:165], v[72:75]
	ds_read_b128 v[162:165], v187 offset:18432
	s_waitcnt lgkmcnt(3)
	v_mfma_f32_16x16x32_bf16 v[116:119], v[148:151], v[166:169], v[116:119]
	v_mfma_f32_16x16x32_bf16 v[100:103], v[152:155], v[166:169], v[100:103]
	v_mfma_f32_16x16x32_bf16 v[84:87], v[244:247], v[166:169], v[84:87]
	v_mfma_f32_16x16x32_bf16 v[68:71], v[248:251], v[166:169], v[68:71]
	ds_read_b128 v[166:169], v187 offset:20480
	s_waitcnt lgkmcnt(3)
	v_mfma_f32_16x16x32_bf16 v[112:115], v[148:151], v[170:173], v[112:115]
	v_mfma_f32_16x16x32_bf16 v[96:99], v[152:155], v[170:173], v[96:99]
	v_mfma_f32_16x16x32_bf16 v[80:83], v[244:247], v[170:173], v[80:83]
	v_mfma_f32_16x16x32_bf16 v[64:67], v[248:251], v[170:173], v[64:67]
	ds_read_b128 v[170:173], v187 offset:22528
	s_waitcnt lgkmcnt(3)
	v_mfma_f32_16x16x32_bf16 v[60:63], v[148:151], v[158:161], v[60:63]
	v_mfma_f32_16x16x32_bf16 v[36:39], v[152:155], v[158:161], v[36:39]
	v_mfma_f32_16x16x32_bf16 v[20:23], v[244:247], v[158:161], v[20:23]
	v_mfma_f32_16x16x32_bf16 v[4:7], v[248:251], v[158:161], v[4:7]
	s_add_u32 s52, s52, 0x80
	s_addc_u32 s53, s53, 0
	s_cmpk_eq_i32 s52, 0xf80
	s_waitcnt vmcnt(0) lgkmcnt(0)
	s_barrier
	s_cbranch_scc1 .Lgemm_698_exit
	s_xor_b32 s62, s59, 0x8000
	v_add3_u32 v157, v138, v143, s62
	v_add3_u32 v186, v140, v143, s62
	ds_read_b128 v[174:177], v157
	ds_read_b128 v[178:181], v157 offset:2048
	ds_read_b128 v[182:185], v157 offset:4096
	ds_read_b128 v[144:147], v157 offset:6144
	ds_read_b128 v[158:161], v186
	s_add_i32 s63, s57, s59
	s_add_i32 s64, s58, s59
	s_lshr_b32 s62, s23, 3
	s_and_b32 s62, s62, 7
	s_lshl_b32 s62, s62, 9
	s_add_i32 vcc_lo, s52, s62
	s_cmp_ge_u32 vcc_lo, 0xf80
	s_cselect_b32 vcc_hi, 0xf80, 0
	s_sub_i32 vcc_lo, vcc_lo, vcc_hi
	v_mfma_f32_16x16x32_bf16 v[56:59], v[148:151], v[162:165], v[56:59]
	v_mfma_f32_16x16x32_bf16 v[32:35], v[152:155], v[162:165], v[32:35]
	v_mfma_f32_16x16x32_bf16 v[16:19], v[244:247], v[162:165], v[16:19]
	v_mfma_f32_16x16x32_bf16 v[0:3], v[248:251], v[162:165], v[0:3]
	ds_read_b128 v[162:165], v186 offset:2048
	s_add_u32 s60, vcc_lo, s24
	s_addc_u32 s61, 0, s25
	s_add_i32 m0, s63, 0x0
	v_lshl_add_u64 v[242:243], v[130:131], 0, s[60:61]
	global_load_lds_dwordx4 v[242:243], off
	s_add_u32 s60, vcc_lo, s26
	s_addc_u32 s61, 0, s27
	s_add_i32 m0, s64, 0x0
	v_lshl_add_u64 v[242:243], v[132:133], 0, s[60:61]
	global_load_lds_dwordx4 v[242:243], off
	v_mfma_f32_16x16x32_bf16 v[52:55], v[148:151], v[166:169], v[52:55]
	v_mfma_f32_16x16x32_bf16 v[28:31], v[152:155], v[166:169], v[28:31]
	v_mfma_f32_16x16x32_bf16 v[12:15], v[244:247], v[166:169], v[12:15]
	v_mfma_f32_16x16x32_bf16 v[44:47], v[248:251], v[166:169], v[44:47]
	ds_read_b128 v[166:169], v186 offset:4096
	s_add_u32 s60, vcc_lo, s36
	s_addc_u32 s61, 0, s37
	s_add_i32 m0, s63, 0x2000
	v_lshl_add_u64 v[242:243], v[130:131], 0, s[60:61]
	global_load_lds_dwordx4 v[242:243], off
	s_add_u32 s60, vcc_lo, s38
	s_addc_u32 s61, 0, s39
	s_add_i32 m0, s64, 0x2000
	v_lshl_add_u64 v[242:243], v[132:133], 0, s[60:61]
	global_load_lds_dwordx4 v[242:243], off
	v_mfma_f32_16x16x32_bf16 v[48:51], v[148:151], v[170:173], v[48:51]
	v_mfma_f32_16x16x32_bf16 v[24:27], v[152:155], v[170:173], v[24:27]
	v_mfma_f32_16x16x32_bf16 v[8:11], v[244:247], v[170:173], v[8:11]
	v_mfma_f32_16x16x32_bf16 v[40:43], v[248:251], v[170:173], v[40:43]
	ds_read_b128 v[170:173], v186 offset:6144
	s_add_u32 s60, vcc_lo, s40
	s_addc_u32 s61, 0, s41
	s_add_i32 m0, s63, 0x4000
	v_lshl_add_u64 v[242:243], v[130:131], 0, s[60:61]
	global_load_lds_dwordx4 v[242:243], off
	s_add_u32 s60, vcc_lo, s42
	s_addc_u32 s61, 0, s43
	s_add_i32 m0, s64, 0x4000
	v_lshl_add_u64 v[242:243], v[132:133], 0, s[60:61]
	global_load_lds_dwordx4 v[242:243], off
	s_branch .LBB0_698
